# lever 1 on a new site: LayerNorm loop-header vmcnt waits moved to the loop entry (back-edge data already guarded by the latch ladder)
# baseline (speedup 1.0000x reference)
; DI int opaque_tid() { int t = threadIdx.x; asm volatile("" : "+v"(t)); return t; }
; DI void ph_ln(const Params& p, int lnidx, bool last) {
;     const int lane = opaque_tid() & 63;
;     const int gw = blockIdx.x * 8 + (opaque_tid() >> 6), nw = gridDim.x * 8;
;     float* H = (float*)(p.ws + OFF_H); bf16_t* HB = (bf16_t*)(p.ws + OFF_HB);
;     const float* G = p.ln_g + (size_t)lnidx * 1024; const float* Bv = p.ln_b + (size_t)lnidx * 1024;
;     f32x4 g[4], bb[4];
; #pragma unroll
;     for (int i = 0; i < 4; ++i) { g[i] = *(const f32x4*)(G + i * 256 + lane * 4); bb[i] = *(const f32x4*)(Bv + i * 256 + lane * 4); }
;     f32x4 nv[4];
;     if (gw < MT) {
; #pragma unroll
;         for (int i = 0; i < 4; ++i) nv[i] = *(const f32x4*)(H + (size_t)gw * 1024 + i * 256 + lane * 4);
;     }
;     for (int m = gw; m < MT; m += nw) {
;         f32x4 v[4];
; #pragma unroll
;         for (int i = 0; i < 4; ++i) v[i] = nv[i];
;         const int mn = min(m + nw, MT - 1);
; #pragma unroll
;         for (int i = 0; i < 4; ++i) nv[i] = *(const f32x4*)(H + (size_t)mn * 1024 + i * 256 + lane * 4);
.LBB0_855:
	s_or_b64 exec, exec, s[0:1]
	s_waitcnt lgkmcnt(0)
	v_mov_b32_e32 v0, v210
	v_mov_b32_e32 v1, v210
	s_barrier
	s_mov_b32 s0, 0x8040
	v_ashrrev_i32_e32 v1, 6, v1
	v_add_u32_e32 v62, s81, v1
	v_cmp_gt_i32_e32 vcc, s0, v62
	s_and_saveexec_b64 s[4:5], vcc
	s_cbranch_execz .LBB0_860
	v_and_b32_e32 v54, 63, v0
	v_lshlrev_b32_e32 v48, 4, v54
	global_load_dwordx4 v[0:3], v48, s[64:65] offset:3072
	global_load_dwordx4 v[4:7], v48, s[62:63] offset:3072
	global_load_dwordx4 v[8:11], v48, s[64:65] offset:2048
	global_load_dwordx4 v[12:15], v48, s[62:63] offset:2048
	v_ashrrev_i32_e32 v63, 31, v62
	v_lshlrev_b64 v[16:17], 12, v[62:63]
	v_mov_b32_e32 v49, 0
	v_lshl_add_u64 v[16:17], s[16:17], 0, v[16:17]
	v_lshl_add_u64 v[50:51], v[16:17], 0, v[48:49]
	global_load_dwordx4 v[44:47], v[50:51], off
	global_load_dwordx4 v[16:19], v48, s[64:65] offset:1024
	global_load_dwordx4 v[20:23], v48, s[62:63] offset:1024
	global_load_dwordx4 v[36:39], v[50:51], off offset:1024
	global_load_dwordx4 v[24:27], v48, s[64:65]
	global_load_dwordx4 v[28:31], v48, s[62:63]
	global_load_dwordx4 v[32:35], v[50:51], off offset:2048
	global_load_dwordx4 v[40:43], v[50:51], off offset:3072
	v_mbcnt_lo_u32_b32 v50, -1, 0
	v_mbcnt_hi_u32_b32 v55, -1, v50
	s_mov_b64 s[0:1], 0x7c00000
	v_lshl_add_u64 v[50:51], v[62:63], 3, s[54:55]
	v_lshl_add_u64 v[64:65], s[16:17], 0, v[48:49]
	v_and_b32_e32 v48, 64, v55
	v_xor_b32_e32 v56, 32, v55
	v_lshl_add_u64 v[66:67], v[50:51], 0, s[0:1]
	v_add_u32_e32 v50, 64, v48
	v_lshlrev_b64 v[52:53], 11, v[62:63]
	v_xor_b32_e32 v57, 16, v55
	v_cmp_lt_i32_e64 s[0:1], v56, v50
	v_xor_b32_e32 v58, 8, v55
	v_lshl_or_b32 v52, v54, 3, v52
	v_cndmask_b32_e64 v51, v55, v56, s[0:1]
	v_cmp_lt_i32_e64 s[0:1], v57, v50
	v_xor_b32_e32 v59, 4, v55
	v_lshl_add_u64 v[48:49], s[56:57], 0, v[52:53]
	v_cndmask_b32_e64 v52, v55, v57, s[0:1]
	v_cmp_lt_i32_e64 s[0:1], v58, v50
	v_xor_b32_e32 v60, 2, v55
	v_cmp_eq_u32_e32 vcc, 0, v54
	v_cndmask_b32_e64 v53, v55, v58, s[0:1]
	v_cmp_lt_i32_e64 s[0:1], v59, v50
	v_xor_b32_e32 v61, 1, v55
	s_ashr_i32 s35, s34, 31
	v_cndmask_b32_e64 v54, v55, v59, s[0:1]
	v_cmp_lt_i32_e64 s[0:1], v60, v50
	s_mov_b64 s[14:15], 0xb840000
	s_mov_b64 s[8:9], 0
	v_cndmask_b32_e64 v56, v55, v60, s[0:1]
	v_cmp_lt_i32_e64 s[0:1], v61, v50
	s_mov_b32 s3, 0x803f
	v_mov_b32_e32 v72, 0x3727c5ac
	v_cndmask_b32_e64 v50, v55, v61, s[0:1]
	s_lshl_b64 s[10:11], s[34:35], 3
	s_lshl_b64 s[12:13], s[34:35], 11
	v_lshl_add_u64 v[68:69], v[48:49], 0, s[14:15]
	v_lshlrev_b32_e32 v63, 2, v51
	v_lshlrev_b32_e32 v73, 2, v52
	v_lshlrev_b32_e32 v74, 2, v53
	v_lshlrev_b32_e32 v75, 2, v54
	v_lshlrev_b32_e32 v76, 2, v56
	v_lshlrev_b32_e32 v77, 2, v50
	s_waitcnt vmcnt(7)
	v_mov_b32_e32 v58, v45
	v_mov_b32_e32 v59, v46
	v_mov_b32_e32 v45, v47
	s_waitcnt vmcnt(4)
	v_mov_b32_e32 v70, v37
	v_mov_b32_e32 v71, v38
	v_mov_b32_e32 v37, v39
	s_waitcnt vmcnt(0)
	s_branch .LBB0_858

; DI unsigned cvt_pk(float lo, float hi) { f32x2 v = {lo, hi}; bf16x2v b = __builtin_convertvector(v, bf16x2v); return __builtin_bit_cast(unsigned, b); }
; DI void ph_ln(const Params& p, int lnidx, bool last) {
;     ...
;     for (int m = gw; m < MT; m += nw) {
;         f32x4 v[4];
; #pragma unroll
;         for (int i = 0; i < 4; ++i) v[i] = nv[i];
;         const int mn = min(m + nw, MT - 1);
; #pragma unroll
;         for (int i = 0; i < 4; ++i) nv[i] = *(const f32x4*)(H + (size_t)mn * 1024 + i * 256 + lane * 4);
;         float s = 0.f;
; #pragma unroll
;         for (int i = 0; i < 4; ++i) s += (v[i][0] + v[i][1]) + (v[i][2] + v[i][3]);
;         for (int o = 32; o > 0; o >>= 1) s += __shfl_xor(s, o);
;         const float mu = s * (1.0f / 1024.0f);
;         float qv = 0.f;
; #pragma unroll
;         for (int i = 0; i < 4; ++i)
; #pragma unroll
;             for (int e = 0; e < 4; ++e) { const float d = v[i][e] - mu; qv += d * d; }
;         for (int o = 32; o > 0; o >>= 1) qv += __shfl_xor(qv, o);
;         const float rstd = __frsqrt_rn(qv * (1.0f / 1024.0f) + 1e-5f);
;         const int b = m / LT, pos = m - b * LT;
; #pragma unroll
;         for (int i = 0; i < 4; ++i) {
;             const int c = i * 256 + lane * 4;
;             f32x4 y;
; #pragma unroll
;             for (int e = 0; e < 4; ++e) y[e] = (v[i][e] - mu) * rstd * g[i][e] + bb[i][e];
;             if (last) {
;                 if (pos >= 16) *(f32x4*)(p.out + ((size_t)b * 8192 + (pos - 16)) * 1024 + c) = y;
;             } else {
;                 u32x2 wv; wv[0] = cvt_pk(y[0], y[1]); wv[1] = cvt_pk(y[2], y[3]);
;                 *(u32x2*)(HB + (size_t)m * 1024 + c) = wv;
;             }
;         }
;         if (!last && lane == 0) ((f32x2*)((unsigned char*)p.out + OFFO_STATS))[m] = (f32x2){mu, rstd};
;     }
.LBB0_858:
	v_pk_add_f32 v[38:39], v[58:59], v[44:45]
	v_pk_add_f32 v[46:47], v[70:71], v[36:37]
	v_add_f32_e32 v38, v38, v39
	v_pk_add_f32 v[46:47], v[46:47], v[46:47] op_sel_hi:[0,1]
	v_add_f32_e32 v39, 0, v38
	v_add_f32_e32 v49, v32, v33
	v_add_f32_e32 v51, v34, v35
	v_mov_b32_e32 v48, v40
	v_mov_b32_e32 v50, v41
	v_mov_b32_e32 v46, v42
	v_mov_b32_e32 v38, v43
	v_pk_add_f32 v[48:49], v[48:49], v[50:51]
	v_pk_add_f32 v[38:39], v[46:47], v[38:39]
	v_add_u32_e32 v62, s34, v62
	v_pk_add_f32 v[38:39], v[48:49], v[38:39]
	v_mov_b32_e32 v78, v59
	v_add_f32_e32 v38, v38, v39
	ds_bpermute_b32 v39, v63, v38
	v_mov_b32_e32 v79, v45
	v_mov_b32_e32 v45, v58
	v_mov_b32_e32 v86, v71
	v_mov_b32_e32 v87, v37
	s_waitcnt lgkmcnt(0)
	v_add_f32_e32 v38, v38, v39
	ds_bpermute_b32 v39, v73, v38
	v_mov_b32_e32 v37, v70
	s_waitcnt lgkmcnt(0)
	v_add_f32_e32 v38, v38, v39
	ds_bpermute_b32 v39, v74, v38
	s_waitcnt lgkmcnt(0)
	v_add_f32_e32 v38, v38, v39
	ds_bpermute_b32 v39, v75, v38
	s_waitcnt lgkmcnt(0)
	v_add_f32_e32 v46, v38, v39
	ds_bpermute_b32 v47, v76, v46
	v_min_i32_e32 v38, 0x803f, v62
	v_ashrrev_i32_e32 v39, 31, v38
	v_lshlrev_b64 v[38:39], 12, v[38:39]
	v_lshl_add_u64 v[38:39], v[64:65], 0, v[38:39]
	s_waitcnt lgkmcnt(0)
	v_add_f32_e32 v80, v46, v47
	global_load_dwordx4 v[58:61], v[38:39], off
	global_load_dwordx4 v[54:57], v[38:39], off offset:1024
	global_load_dwordx4 v[50:53], v[38:39], off offset:2048
	global_load_dwordx4 v[46:49], v[38:39], off offset:3072
	ds_bpermute_b32 v81, v77, v80
	s_waitcnt lgkmcnt(0)
	v_add_f32_e32 v38, v80, v81
	v_mul_f32_e32 v38, 0x3a800000, v38
	v_pk_add_f32 v[44:45], v[44:45], v[38:39] op_sel_hi:[1,0] neg_lo:[0,1] neg_hi:[0,1]
	v_pk_add_f32 v[78:79], v[78:79], v[38:39] op_sel_hi:[1,0] neg_lo:[0,1] neg_hi:[0,1]
	v_pk_mul_f32 v[84:85], v[44:45], v[44:45]
	v_pk_add_f32 v[42:43], v[42:43], v[38:39] op_sel_hi:[1,0] neg_lo:[0,1] neg_hi:[0,1]
	v_pk_mul_f32 v[82:83], v[78:79], v[78:79]
	v_pk_add_f32 v[86:87], v[86:87], v[38:39] op_sel_hi:[1,0] neg_lo:[0,1] neg_hi:[0,1]
	v_pk_add_f32 v[36:37], v[36:37], v[38:39] op_sel_hi:[1,0] neg_lo:[0,1] neg_hi:[0,1]
	v_pk_add_f32 v[34:35], v[34:35], v[38:39] op_sel_hi:[1,0] neg_lo:[0,1] neg_hi:[0,1]
	v_pk_add_f32 v[92:93], v[32:33], v[38:39] op_sel_hi:[1,0] neg_lo:[0,1] neg_hi:[0,1]
	v_pk_add_f32 v[40:41], v[40:41], v[38:39] op_sel_hi:[1,0] neg_lo:[0,1] neg_hi:[0,1]
	v_add_f32_e32 v39, v84, v85
	v_add_f32_e32 v39, v82, v39
	v_pk_mul_f32 v[70:71], v[36:37], v[36:37]
	v_add_f32_e32 v39, v83, v39
	v_add_f32_e32 v39, v70, v39
	v_pk_mul_f32 v[88:89], v[86:87], v[86:87]
	v_add_f32_e32 v39, v71, v39
	v_add_f32_e32 v39, v88, v39
	v_pk_mul_f32 v[32:33], v[92:93], v[92:93]
	v_add_f32_e32 v39, v89, v39
	v_add_f32_e32 v32, v32, v39
	v_pk_mul_f32 v[90:91], v[34:35], v[34:35]
	v_add_f32_e32 v32, v33, v32
	v_add_f32_e32 v32, v90, v32
	v_pk_mul_f32 v[94:95], v[40:41], v[40:41]
	v_add_f32_e32 v32, v91, v32
	v_add_f32_e32 v32, v94, v32
	v_pk_mul_f32 v[80:81], v[42:43], v[42:43]
	v_add_f32_e32 v32, v95, v32
	v_add_f32_e32 v32, v80, v32
	v_add_f32_e32 v32, v81, v32
	ds_bpermute_b32 v33, v63, v32
	s_waitcnt lgkmcnt(0)
	v_add_f32_e32 v32, v32, v33
	ds_bpermute_b32 v33, v73, v32
	s_waitcnt lgkmcnt(0)
	v_add_f32_e32 v32, v32, v33
	ds_bpermute_b32 v33, v74, v32
	s_waitcnt lgkmcnt(0)
	v_add_f32_e32 v32, v32, v33
	ds_bpermute_b32 v33, v75, v32
	s_waitcnt lgkmcnt(0)
	v_add_f32_e32 v32, v32, v33
	ds_bpermute_b32 v33, v76, v32
	s_waitcnt lgkmcnt(0)
	v_add_f32_e32 v32, v32, v33
	ds_bpermute_b32 v33, v77, v32
	s_waitcnt lgkmcnt(0)
	v_add_f32_e32 v32, v32, v33
	v_fmamk_f32 v32, v32, 0x3a800000, v72
	v_rsq_f32_e32 v32, v32
	s_nop 0
	v_pk_mul_f32 v[44:45], v[44:45], v[32:33] op_sel_hi:[1,0]
	v_pk_mul_f32 v[70:71], v[78:79], v[32:33] op_sel_hi:[1,0]
	v_pk_mul_f32 v[36:37], v[36:37], v[32:33] op_sel_hi:[1,0]
	v_pk_mul_f32 v[78:79], v[86:87], v[32:33] op_sel_hi:[1,0]
	v_pk_mul_f32 v[80:81], v[92:93], v[32:33] op_sel_hi:[1,0]
	v_pk_mul_f32 v[34:35], v[34:35], v[32:33] op_sel_hi:[1,0]
	v_pk_fma_f32 v[44:45], v[28:29], v[44:45], v[24:25]
	v_pk_fma_f32 v[70:71], v[30:31], v[70:71], v[26:27]
	v_pk_fma_f32 v[36:37], v[20:21], v[36:37], v[16:17]
	v_pk_fma_f32 v[78:79], v[22:23], v[78:79], v[18:19]
	v_pk_fma_f32 v[80:81], v[12:13], v[80:81], v[8:9]
	v_cvt_pk_bf16_f32 v44, v44, v45
	v_cvt_pk_bf16_f32 v45, v70, v71
	v_cvt_pk_bf16_f32 v36, v36, v37
	v_cvt_pk_bf16_f32 v37, v78, v79
	v_pk_fma_f32 v[34:35], v[14:15], v[34:35], v[10:11]
	global_store_dwordx2 v[68:69], v[44:45], off
	global_store_dwordx2 v[68:69], v[36:37], off offset:512
	v_cvt_pk_bf16_f32 v36, v80, v81
	v_cvt_pk_bf16_f32 v37, v34, v35
	global_store_dwordx2 v[68:69], v[36:37], off offset:1024
	v_pk_mul_f32 v[34:35], v[40:41], v[32:33] op_sel_hi:[1,0]
	v_pk_mul_f32 v[36:37], v[42:43], v[32:33] op_sel_hi:[1,0]
	v_pk_fma_f32 v[34:35], v[4:5], v[34:35], v[0:1]
	v_pk_fma_f32 v[36:37], v[6:7], v[36:37], v[2:3]
	v_cvt_pk_bf16_f32 v34, v34, v35
	v_cvt_pk_bf16_f32 v35, v36, v37
	global_store_dwordx2 v[68:69], v[34:35], off offset:1536
	s_and_saveexec_b64 s[0:1], vcc
	s_cbranch_execz .LBB0_857
	v_mov_b32_e32 v39, v32
	global_store_dwordx2 v[66:67], v[38:39], off
	s_branch .LBB0_857

; DI int opaque_tid() { int t = threadIdx.x; asm volatile("" : "+v"(t)); return t; }
; DI void ph_ln(const Params& p, int lnidx, bool last) {
;     const int lane = opaque_tid() & 63;
;     const int gw = blockIdx.x * 8 + (opaque_tid() >> 6), nw = gridDim.x * 8;
;     float* H = (float*)(p.ws + OFF_H); bf16_t* HB = (bf16_t*)(p.ws + OFF_HB);
;     const float* G = p.ln_g + (size_t)lnidx * 1024; const float* Bv = p.ln_b + (size_t)lnidx * 1024;
;     f32x4 g[4], bb[4];
; #pragma unroll
;     for (int i = 0; i < 4; ++i) { g[i] = *(const f32x4*)(G + i * 256 + lane * 4); bb[i] = *(const f32x4*)(Bv + i * 256 + lane * 4); }
;     f32x4 nv[4];
;     if (gw < MT) {
; #pragma unroll
;         for (int i = 0; i < 4; ++i) nv[i] = *(const f32x4*)(H + (size_t)gw * 1024 + i * 256 + lane * 4);
;     }
;     for (int m = gw; m < MT; m += nw) {
;         f32x4 v[4];
; #pragma unroll
;         for (int i = 0; i < 4; ++i) v[i] = nv[i];
;         const int mn = min(m + nw, MT - 1);
; #pragma unroll
;         for (int i = 0; i < 4; ++i) nv[i] = *(const f32x4*)(H + (size_t)mn * 1024 + i * 256 + lane * 4);
.LBB0_1068:
	s_or_b64 exec, exec, s[4:5]
	s_waitcnt lgkmcnt(0)
	v_mov_b32_e32 v0, v210
	v_mov_b32_e32 v1, v210
	s_barrier
	s_mov_b32 s3, 0x8040
	v_ashrrev_i32_e32 v1, 6, v1
	v_add_u32_e32 v62, s81, v1
	v_cmp_gt_i32_e32 vcc, s3, v62
	s_and_saveexec_b64 s[6:7], vcc
	s_cbranch_execz .LBB0_1073
	v_and_b32_e32 v54, 63, v0
	v_lshlrev_b32_e32 v48, 4, v54
	v_mov_b32_e32 v49, 0
	v_lshl_add_u64 v[24:25], s[64:65], 0, v[48:49]
	s_mov_b64 s[4:5], 0x1000
	v_lshl_add_u64 v[28:29], s[62:63], 0, v[48:49]
	v_lshl_add_u64 v[26:27], v[24:25], 0, s[4:5]
	v_lshl_add_u64 v[30:31], v[28:29], 0, s[4:5]
	v_ashrrev_i32_e32 v63, 31, v62
	global_load_dwordx4 v[0:3], v[26:27], off offset:3072
	global_load_dwordx4 v[4:7], v[30:31], off offset:3072
	global_load_dwordx4 v[8:11], v[26:27], off offset:2048
	global_load_dwordx4 v[12:15], v[26:27], off offset:1024
	global_load_dwordx4 v[16:19], v[30:31], off offset:2048
	global_load_dwordx4 v[20:23], v[30:31], off offset:1024
	v_lshlrev_b64 v[30:31], 12, v[62:63]
	v_lshl_add_u64 v[30:31], s[16:17], 0, v[30:31]
	v_add_co_u32_e32 v24, vcc, 0x1000, v24
	v_lshl_add_u64 v[52:53], v[30:31], 0, v[48:49]
	s_nop 0
	v_addc_co_u32_e32 v25, vcc, 0, v25, vcc
	global_load_dwordx4 v[44:47], v[52:53], off
	v_add_co_u32_e32 v50, vcc, 0x1000, v28
	global_load_dwordx4 v[24:27], v[24:25], off
	s_nop 0
	v_addc_co_u32_e32 v51, vcc, 0, v29, vcc
	global_load_dwordx4 v[36:39], v[52:53], off offset:1024
	global_load_dwordx4 v[32:35], v[52:53], off offset:2048
	global_load_dwordx4 v[40:43], v[52:53], off offset:3072
	global_load_dwordx4 v[28:31], v[50:51], off
	v_mbcnt_lo_u32_b32 v50, -1, 0
	v_mbcnt_hi_u32_b32 v55, -1, v50
	s_mov_b64 s[4:5], 0x7c00000
	v_lshl_add_u64 v[50:51], v[62:63], 3, s[54:55]
	v_lshl_add_u64 v[64:65], s[16:17], 0, v[48:49]
	v_and_b32_e32 v48, 64, v55
	v_xor_b32_e32 v56, 32, v55
	v_lshl_add_u64 v[66:67], v[50:51], 0, s[4:5]
	v_add_u32_e32 v50, 64, v48
	v_lshlrev_b64 v[52:53], 11, v[62:63]
	v_xor_b32_e32 v57, 16, v55
	v_cmp_lt_i32_e64 s[4:5], v56, v50
	v_xor_b32_e32 v58, 8, v55
	v_lshl_or_b32 v52, v54, 3, v52
	v_cndmask_b32_e64 v51, v55, v56, s[4:5]
	v_cmp_lt_i32_e64 s[4:5], v57, v50
	v_xor_b32_e32 v59, 4, v55
	v_lshl_add_u64 v[48:49], s[56:57], 0, v[52:53]
	v_cndmask_b32_e64 v52, v55, v57, s[4:5]
	v_cmp_lt_i32_e64 s[4:5], v58, v50
	v_xor_b32_e32 v60, 2, v55
	v_cmp_eq_u32_e32 vcc, 0, v54
	v_cndmask_b32_e64 v53, v55, v58, s[4:5]
	v_cmp_lt_i32_e64 s[4:5], v59, v50
	v_xor_b32_e32 v61, 1, v55
	s_ashr_i32 s35, s34, 31
	v_cndmask_b32_e64 v54, v55, v59, s[4:5]
	v_cmp_lt_i32_e64 s[4:5], v60, v50
	s_mov_b64 s[14:15], 0xb840000
	s_mov_b64 s[8:9], 0
	v_cndmask_b32_e64 v56, v55, v60, s[4:5]
	v_cmp_lt_i32_e64 s[4:5], v61, v50
	s_mov_b32 s3, 0x803f
	v_mov_b32_e32 v72, 0x3727c5ac
	v_cndmask_b32_e64 v50, v55, v61, s[4:5]
	s_lshl_b64 s[10:11], s[34:35], 3
	s_lshl_b64 s[12:13], s[34:35], 11
	v_lshl_add_u64 v[68:69], v[48:49], 0, s[14:15]
	v_lshlrev_b32_e32 v63, 2, v51
	v_lshlrev_b32_e32 v73, 2, v52
	v_lshlrev_b32_e32 v74, 2, v53
	v_lshlrev_b32_e32 v75, 2, v54
	v_lshlrev_b32_e32 v76, 2, v56
	v_lshlrev_b32_e32 v77, 2, v50
	s_waitcnt vmcnt(5)
	v_mov_b32_e32 v58, v45
	v_mov_b32_e32 v59, v46
	v_mov_b32_e32 v45, v47
	s_waitcnt vmcnt(3)
	v_mov_b32_e32 v70, v37
	v_mov_b32_e32 v71, v38
	v_mov_b32_e32 v37, v39
	s_waitcnt vmcnt(0)
	s_branch .LBB0_1071

; DI unsigned cvt_pk(float lo, float hi) { f32x2 v = {lo, hi}; bf16x2v b = __builtin_convertvector(v, bf16x2v); return __builtin_bit_cast(unsigned, b); }
; DI void ph_ln(const Params& p, int lnidx, bool last) {
;     ...
;     for (int m = gw; m < MT; m += nw) {
;         f32x4 v[4];
; #pragma unroll
;         for (int i = 0; i < 4; ++i) v[i] = nv[i];
;         const int mn = min(m + nw, MT - 1);
; #pragma unroll
;         for (int i = 0; i < 4; ++i) nv[i] = *(const f32x4*)(H + (size_t)mn * 1024 + i * 256 + lane * 4);
;         float s = 0.f;
; #pragma unroll
;         for (int i = 0; i < 4; ++i) s += (v[i][0] + v[i][1]) + (v[i][2] + v[i][3]);
;         for (int o = 32; o > 0; o >>= 1) s += __shfl_xor(s, o);
;         const float mu = s * (1.0f / 1024.0f);
;         float qv = 0.f;
; #pragma unroll
;         for (int i = 0; i < 4; ++i)
; #pragma unroll
;             for (int e = 0; e < 4; ++e) { const float d = v[i][e] - mu; qv += d * d; }
;         for (int o = 32; o > 0; o >>= 1) qv += __shfl_xor(qv, o);
;         const float rstd = __frsqrt_rn(qv * (1.0f / 1024.0f) + 1e-5f);
;         const int b = m / LT, pos = m - b * LT;
; #pragma unroll
;         for (int i = 0; i < 4; ++i) {
;             const int c = i * 256 + lane * 4;
;             f32x4 y;
; #pragma unroll
;             for (int e = 0; e < 4; ++e) y[e] = (v[i][e] - mu) * rstd * g[i][e] + bb[i][e];
;             if (last) {
;                 if (pos >= 16) *(f32x4*)(p.out + ((size_t)b * 8192 + (pos - 16)) * 1024 + c) = y;
;             } else {
;                 u32x2 wv; wv[0] = cvt_pk(y[0], y[1]); wv[1] = cvt_pk(y[2], y[3]);
;                 *(u32x2*)(HB + (size_t)m * 1024 + c) = wv;
;             }
;         }
;         if (!last && lane == 0) ((f32x2*)((unsigned char*)p.out + OFFO_STATS))[m] = (f32x2){mu, rstd};
;     }
.LBB0_1071:
	v_pk_add_f32 v[38:39], v[58:59], v[44:45]
	v_pk_add_f32 v[46:47], v[70:71], v[36:37]
	v_add_f32_e32 v38, v38, v39
	v_pk_add_f32 v[46:47], v[46:47], v[46:47] op_sel_hi:[0,1]
	v_add_f32_e32 v39, 0, v38
	v_add_f32_e32 v49, v32, v33
	v_add_f32_e32 v51, v34, v35
	v_mov_b32_e32 v48, v40
	v_mov_b32_e32 v50, v41
	v_mov_b32_e32 v46, v42
	v_mov_b32_e32 v38, v43
	v_pk_add_f32 v[48:49], v[48:49], v[50:51]
	v_pk_add_f32 v[38:39], v[46:47], v[38:39]
	v_add_u32_e32 v62, s34, v62
	v_pk_add_f32 v[38:39], v[48:49], v[38:39]
	v_mov_b32_e32 v78, v59
	v_add_f32_e32 v38, v38, v39
	ds_bpermute_b32 v39, v63, v38
	v_mov_b32_e32 v79, v45
	v_mov_b32_e32 v45, v58
	v_mov_b32_e32 v86, v71
	v_mov_b32_e32 v87, v37
	s_waitcnt lgkmcnt(0)
	v_add_f32_e32 v38, v38, v39
	ds_bpermute_b32 v39, v73, v38
	v_mov_b32_e32 v37, v70
	s_waitcnt lgkmcnt(0)
	v_add_f32_e32 v38, v38, v39
	ds_bpermute_b32 v39, v74, v38
	s_waitcnt lgkmcnt(0)
	v_add_f32_e32 v38, v38, v39
	ds_bpermute_b32 v39, v75, v38
	s_waitcnt lgkmcnt(0)
	v_add_f32_e32 v46, v38, v39
	ds_bpermute_b32 v47, v76, v46
	v_min_i32_e32 v38, 0x803f, v62
	v_ashrrev_i32_e32 v39, 31, v38
	v_lshlrev_b64 v[38:39], 12, v[38:39]
	v_lshl_add_u64 v[38:39], v[64:65], 0, v[38:39]
	s_waitcnt lgkmcnt(0)
	v_add_f32_e32 v80, v46, v47
	global_load_dwordx4 v[58:61], v[38:39], off
	global_load_dwordx4 v[54:57], v[38:39], off offset:1024
	global_load_dwordx4 v[50:53], v[38:39], off offset:2048
	global_load_dwordx4 v[46:49], v[38:39], off offset:3072
	ds_bpermute_b32 v81, v77, v80
	s_waitcnt lgkmcnt(0)
	v_add_f32_e32 v38, v80, v81
	v_mul_f32_e32 v38, 0x3a800000, v38
	v_pk_add_f32 v[44:45], v[44:45], v[38:39] op_sel_hi:[1,0] neg_lo:[0,1] neg_hi:[0,1]
	v_pk_add_f32 v[78:79], v[78:79], v[38:39] op_sel_hi:[1,0] neg_lo:[0,1] neg_hi:[0,1]
	v_pk_mul_f32 v[84:85], v[44:45], v[44:45]
	v_pk_add_f32 v[42:43], v[42:43], v[38:39] op_sel_hi:[1,0] neg_lo:[0,1] neg_hi:[0,1]
	v_pk_mul_f32 v[82:83], v[78:79], v[78:79]
	v_pk_add_f32 v[86:87], v[86:87], v[38:39] op_sel_hi:[1,0] neg_lo:[0,1] neg_hi:[0,1]
	v_pk_add_f32 v[36:37], v[36:37], v[38:39] op_sel_hi:[1,0] neg_lo:[0,1] neg_hi:[0,1]
	v_pk_add_f32 v[34:35], v[34:35], v[38:39] op_sel_hi:[1,0] neg_lo:[0,1] neg_hi:[0,1]
	v_pk_add_f32 v[92:93], v[32:33], v[38:39] op_sel_hi:[1,0] neg_lo:[0,1] neg_hi:[0,1]
	v_pk_add_f32 v[40:41], v[40:41], v[38:39] op_sel_hi:[1,0] neg_lo:[0,1] neg_hi:[0,1]
	v_add_f32_e32 v39, v84, v85
	v_add_f32_e32 v39, v82, v39
	v_pk_mul_f32 v[70:71], v[36:37], v[36:37]
	v_add_f32_e32 v39, v83, v39
	v_add_f32_e32 v39, v70, v39
	v_pk_mul_f32 v[88:89], v[86:87], v[86:87]
	v_add_f32_e32 v39, v71, v39
	v_add_f32_e32 v39, v88, v39
	v_pk_mul_f32 v[32:33], v[92:93], v[92:93]
	v_add_f32_e32 v39, v89, v39
	v_add_f32_e32 v32, v32, v39
	v_pk_mul_f32 v[90:91], v[34:35], v[34:35]
	v_add_f32_e32 v32, v33, v32
	v_add_f32_e32 v32, v90, v32
	v_pk_mul_f32 v[94:95], v[40:41], v[40:41]
	v_add_f32_e32 v32, v91, v32
	v_add_f32_e32 v32, v94, v32
	v_pk_mul_f32 v[80:81], v[42:43], v[42:43]
	v_add_f32_e32 v32, v95, v32
	v_add_f32_e32 v32, v80, v32
	v_add_f32_e32 v32, v81, v32
	ds_bpermute_b32 v33, v63, v32
	s_waitcnt lgkmcnt(0)
	v_add_f32_e32 v32, v32, v33
	ds_bpermute_b32 v33, v73, v32
	s_waitcnt lgkmcnt(0)
	v_add_f32_e32 v32, v32, v33
	ds_bpermute_b32 v33, v74, v32
	s_waitcnt lgkmcnt(0)
	v_add_f32_e32 v32, v32, v33
	ds_bpermute_b32 v33, v75, v32
	s_waitcnt lgkmcnt(0)
	v_add_f32_e32 v32, v32, v33
	ds_bpermute_b32 v33, v76, v32
	s_waitcnt lgkmcnt(0)
	v_add_f32_e32 v32, v32, v33
	ds_bpermute_b32 v33, v77, v32
	s_waitcnt lgkmcnt(0)
	v_add_f32_e32 v32, v32, v33
	v_fmamk_f32 v32, v32, 0x3a800000, v72
	v_rsq_f32_e32 v32, v32
	s_nop 0
	v_pk_mul_f32 v[44:45], v[44:45], v[32:33] op_sel_hi:[1,0]
	v_pk_mul_f32 v[70:71], v[78:79], v[32:33] op_sel_hi:[1,0]
	v_pk_mul_f32 v[36:37], v[36:37], v[32:33] op_sel_hi:[1,0]
	v_pk_mul_f32 v[78:79], v[86:87], v[32:33] op_sel_hi:[1,0]
	v_pk_mul_f32 v[80:81], v[92:93], v[32:33] op_sel_hi:[1,0]
	v_pk_mul_f32 v[34:35], v[34:35], v[32:33] op_sel_hi:[1,0]
	s_waitcnt vmcnt(4)
	v_pk_fma_f32 v[44:45], v[28:29], v[44:45], v[24:25]
	v_pk_fma_f32 v[70:71], v[30:31], v[70:71], v[26:27]
	v_pk_fma_f32 v[36:37], v[20:21], v[36:37], v[12:13]
	v_pk_fma_f32 v[78:79], v[22:23], v[78:79], v[14:15]
	v_pk_fma_f32 v[80:81], v[16:17], v[80:81], v[8:9]
	v_cvt_pk_bf16_f32 v44, v44, v45
	v_cvt_pk_bf16_f32 v45, v70, v71
	v_cvt_pk_bf16_f32 v36, v36, v37
	v_cvt_pk_bf16_f32 v37, v78, v79
	v_pk_fma_f32 v[34:35], v[18:19], v[34:35], v[10:11]
	global_store_dwordx2 v[68:69], v[44:45], off
	global_store_dwordx2 v[68:69], v[36:37], off offset:512
	v_cvt_pk_bf16_f32 v36, v80, v81
	v_cvt_pk_bf16_f32 v37, v34, v35
	global_store_dwordx2 v[68:69], v[36:37], off offset:1024
	v_pk_mul_f32 v[34:35], v[40:41], v[32:33] op_sel_hi:[1,0]
	v_pk_mul_f32 v[36:37], v[42:43], v[32:33] op_sel_hi:[1,0]
	v_pk_fma_f32 v[34:35], v[4:5], v[34:35], v[0:1]
	v_pk_fma_f32 v[36:37], v[6:7], v[36:37], v[2:3]
	v_cvt_pk_bf16_f32 v34, v34, v35
	v_cvt_pk_bf16_f32 v35, v36, v37
	global_store_dwordx2 v[68:69], v[34:35], off offset:1536
	s_and_saveexec_b64 s[4:5], vcc
	s_cbranch_execz .LBB0_1070
	v_mov_b32_e32 v39, v32
	global_store_dwordx2 v[66:67], v[38:39], off
	s_branch .LBB0_1070

; DI int opaque_tid() { int t = threadIdx.x; asm volatile("" : "+v"(t)); return t; }
; DI void ph_ln(const Params& p, int lnidx, bool last) {
;     const int lane = opaque_tid() & 63;
;     const int gw = blockIdx.x * 8 + (opaque_tid() >> 6), nw = gridDim.x * 8;
;     float* H = (float*)(p.ws + OFF_H); bf16_t* HB = (bf16_t*)(p.ws + OFF_HB);
;     const float* G = p.ln_g + (size_t)lnidx * 1024; const float* Bv = p.ln_b + (size_t)lnidx * 1024;
;     f32x4 g[4], bb[4];
; #pragma unroll
;     for (int i = 0; i < 4; ++i) { g[i] = *(const f32x4*)(G + i * 256 + lane * 4); bb[i] = *(const f32x4*)(Bv + i * 256 + lane * 4); }
;     f32x4 nv[4];
;     if (gw < MT) {
; #pragma unroll
;         for (int i = 0; i < 4; ++i) nv[i] = *(const f32x4*)(H + (size_t)gw * 1024 + i * 256 + lane * 4);
;     }
;     for (int m = gw; m < MT; m += nw) {
;         f32x4 v[4];
; #pragma unroll
;         for (int i = 0; i < 4; ++i) v[i] = nv[i];
;         const int mn = min(m + nw, MT - 1);
; #pragma unroll
;         for (int i = 0; i < 4; ++i) nv[i] = *(const f32x4*)(H + (size_t)mn * 1024 + i * 256 + lane * 4);
.LBB0_1780:
	s_or_b64 exec, exec, s[6:7]
	s_waitcnt lgkmcnt(0)
	v_mov_b32_e32 v0, v210
	v_mov_b32_e32 v1, v210
	s_barrier
	s_mov_b32 s3, 0x8040
	v_ashrrev_i32_e32 v1, 6, v1
	v_add_u32_e32 v62, s81, v1
	v_cmp_gt_i32_e32 vcc, s3, v62
	s_and_saveexec_b64 s[8:9], vcc
	s_cbranch_execz .LBB0_1785
	v_and_b32_e32 v54, 63, v0
	v_lshlrev_b32_e32 v48, 4, v54
	v_mov_b32_e32 v49, 0
	v_lshl_add_u64 v[24:25], s[64:65], 0, v[48:49]
	s_mov_b64 s[6:7], 0x2000
	v_lshl_add_u64 v[28:29], s[62:63], 0, v[48:49]
	v_lshl_add_u64 v[26:27], v[24:25], 0, s[6:7]
	v_lshl_add_u64 v[30:31], v[28:29], 0, s[6:7]
	v_ashrrev_i32_e32 v63, 31, v62
	global_load_dwordx4 v[0:3], v[26:27], off offset:3072
	global_load_dwordx4 v[4:7], v[30:31], off offset:3072
	global_load_dwordx4 v[8:11], v[26:27], off offset:2048
	global_load_dwordx4 v[12:15], v[26:27], off offset:1024
	global_load_dwordx4 v[16:19], v[30:31], off offset:2048
	global_load_dwordx4 v[20:23], v[30:31], off offset:1024
	v_lshlrev_b64 v[30:31], 12, v[62:63]
	v_lshl_add_u64 v[30:31], s[16:17], 0, v[30:31]
	v_add_co_u32_e32 v24, vcc, 0x2000, v24
	v_lshl_add_u64 v[52:53], v[30:31], 0, v[48:49]
	s_nop 0
	v_addc_co_u32_e32 v25, vcc, 0, v25, vcc
	global_load_dwordx4 v[44:47], v[52:53], off
	v_add_co_u32_e32 v50, vcc, 0x2000, v28
	global_load_dwordx4 v[24:27], v[24:25], off
	s_nop 0
	v_addc_co_u32_e32 v51, vcc, 0, v29, vcc
	global_load_dwordx4 v[36:39], v[52:53], off offset:1024
	global_load_dwordx4 v[32:35], v[52:53], off offset:2048
	global_load_dwordx4 v[40:43], v[52:53], off offset:3072
	global_load_dwordx4 v[28:31], v[50:51], off
	v_mbcnt_lo_u32_b32 v50, -1, 0
	v_mbcnt_hi_u32_b32 v55, -1, v50
	s_mov_b64 s[6:7], 0x7c00000
	v_lshl_add_u64 v[50:51], v[62:63], 3, s[54:55]
	v_lshl_add_u64 v[64:65], s[16:17], 0, v[48:49]
	v_and_b32_e32 v48, 64, v55
	v_xor_b32_e32 v56, 32, v55
	v_lshl_add_u64 v[66:67], v[50:51], 0, s[6:7]
	v_add_u32_e32 v50, 64, v48
	v_lshlrev_b64 v[52:53], 11, v[62:63]
	v_xor_b32_e32 v57, 16, v55
	v_cmp_lt_i32_e64 s[6:7], v56, v50
	v_xor_b32_e32 v58, 8, v55
	v_lshl_or_b32 v52, v54, 3, v52
	v_cndmask_b32_e64 v51, v55, v56, s[6:7]
	v_cmp_lt_i32_e64 s[6:7], v57, v50
	v_xor_b32_e32 v59, 4, v55
	v_lshl_add_u64 v[48:49], s[56:57], 0, v[52:53]
	v_cndmask_b32_e64 v52, v55, v57, s[6:7]
	v_cmp_lt_i32_e64 s[6:7], v58, v50
	v_xor_b32_e32 v60, 2, v55
	v_cmp_eq_u32_e32 vcc, 0, v54
	v_cndmask_b32_e64 v53, v55, v58, s[6:7]
	v_cmp_lt_i32_e64 s[6:7], v59, v50
	v_xor_b32_e32 v61, 1, v55
	s_ashr_i32 s35, s34, 31
	v_cndmask_b32_e64 v54, v55, v59, s[6:7]
	v_cmp_lt_i32_e64 s[6:7], v60, v50
	s_mov_b64 s[20:21], 0xb840000
	s_mov_b64 s[10:11], 0
	v_cndmask_b32_e64 v56, v55, v60, s[6:7]
	v_cmp_lt_i32_e64 s[6:7], v61, v50
	s_mov_b32 s3, 0x803f
	v_mov_b32_e32 v72, 0x3727c5ac
	v_cndmask_b32_e64 v50, v55, v61, s[6:7]
	s_lshl_b64 s[12:13], s[34:35], 3
	s_lshl_b64 s[14:15], s[34:35], 11
	v_lshl_add_u64 v[68:69], v[48:49], 0, s[20:21]
	v_lshlrev_b32_e32 v63, 2, v51
	v_lshlrev_b32_e32 v73, 2, v52
	v_lshlrev_b32_e32 v74, 2, v53
	v_lshlrev_b32_e32 v75, 2, v54
	v_lshlrev_b32_e32 v76, 2, v56
	v_lshlrev_b32_e32 v77, 2, v50
	s_waitcnt vmcnt(5)
	v_mov_b32_e32 v58, v45
	v_mov_b32_e32 v59, v46
	v_mov_b32_e32 v45, v47
	s_waitcnt vmcnt(3)
	v_mov_b32_e32 v70, v37
	v_mov_b32_e32 v71, v38
	v_mov_b32_e32 v37, v39
	s_waitcnt vmcnt(0)
	s_branch .LBB0_1783

; DI unsigned cvt_pk(float lo, float hi) { f32x2 v = {lo, hi}; bf16x2v b = __builtin_convertvector(v, bf16x2v); return __builtin_bit_cast(unsigned, b); }
; DI void ph_ln(const Params& p, int lnidx, bool last) {
;     ...
;     for (int m = gw; m < MT; m += nw) {
;         f32x4 v[4];
; #pragma unroll
;         for (int i = 0; i < 4; ++i) v[i] = nv[i];
;         const int mn = min(m + nw, MT - 1);
; #pragma unroll
;         for (int i = 0; i < 4; ++i) nv[i] = *(const f32x4*)(H + (size_t)mn * 1024 + i * 256 + lane * 4);
;         float s = 0.f;
; #pragma unroll
;         for (int i = 0; i < 4; ++i) s += (v[i][0] + v[i][1]) + (v[i][2] + v[i][3]);
;         for (int o = 32; o > 0; o >>= 1) s += __shfl_xor(s, o);
;         const float mu = s * (1.0f / 1024.0f);
;         float qv = 0.f;
; #pragma unroll
;         for (int i = 0; i < 4; ++i)
; #pragma unroll
;             for (int e = 0; e < 4; ++e) { const float d = v[i][e] - mu; qv += d * d; }
;         for (int o = 32; o > 0; o >>= 1) qv += __shfl_xor(qv, o);
;         const float rstd = __frsqrt_rn(qv * (1.0f / 1024.0f) + 1e-5f);
;         const int b = m / LT, pos = m - b * LT;
; #pragma unroll
;         for (int i = 0; i < 4; ++i) {
;             const int c = i * 256 + lane * 4;
;             f32x4 y;
; #pragma unroll
;             for (int e = 0; e < 4; ++e) y[e] = (v[i][e] - mu) * rstd * g[i][e] + bb[i][e];
;             if (last) {
;                 if (pos >= 16) *(f32x4*)(p.out + ((size_t)b * 8192 + (pos - 16)) * 1024 + c) = y;
;             } else {
;                 u32x2 wv; wv[0] = cvt_pk(y[0], y[1]); wv[1] = cvt_pk(y[2], y[3]);
;                 *(u32x2*)(HB + (size_t)m * 1024 + c) = wv;
;             }
;         }
;         if (!last && lane == 0) ((f32x2*)((unsigned char*)p.out + OFFO_STATS))[m] = (f32x2){mu, rstd};
;     }
.LBB0_1783:
	v_pk_add_f32 v[38:39], v[58:59], v[44:45]
	v_pk_add_f32 v[46:47], v[70:71], v[36:37]
	v_add_f32_e32 v38, v38, v39
	v_pk_add_f32 v[46:47], v[46:47], v[46:47] op_sel_hi:[0,1]
	v_add_f32_e32 v39, 0, v38
	v_add_f32_e32 v49, v32, v33
	v_add_f32_e32 v51, v34, v35
	v_mov_b32_e32 v48, v40
	v_mov_b32_e32 v50, v41
	v_mov_b32_e32 v46, v42
	v_mov_b32_e32 v38, v43
	v_pk_add_f32 v[48:49], v[48:49], v[50:51]
	v_pk_add_f32 v[38:39], v[46:47], v[38:39]
	v_add_u32_e32 v62, s34, v62
	v_pk_add_f32 v[38:39], v[48:49], v[38:39]
	v_mov_b32_e32 v78, v59
	v_add_f32_e32 v38, v38, v39
	ds_bpermute_b32 v39, v63, v38
	v_mov_b32_e32 v79, v45
	v_mov_b32_e32 v45, v58
	v_mov_b32_e32 v86, v71
	v_mov_b32_e32 v87, v37
	s_waitcnt lgkmcnt(0)
	v_add_f32_e32 v38, v38, v39
	ds_bpermute_b32 v39, v73, v38
	v_mov_b32_e32 v37, v70
	s_waitcnt lgkmcnt(0)
	v_add_f32_e32 v38, v38, v39
	ds_bpermute_b32 v39, v74, v38
	s_waitcnt lgkmcnt(0)
	v_add_f32_e32 v38, v38, v39
	ds_bpermute_b32 v39, v75, v38
	s_waitcnt lgkmcnt(0)
	v_add_f32_e32 v46, v38, v39
	ds_bpermute_b32 v47, v76, v46
	v_min_i32_e32 v38, 0x803f, v62
	v_ashrrev_i32_e32 v39, 31, v38
	v_lshlrev_b64 v[38:39], 12, v[38:39]
	v_lshl_add_u64 v[38:39], v[64:65], 0, v[38:39]
	s_waitcnt lgkmcnt(0)
	v_add_f32_e32 v80, v46, v47
	global_load_dwordx4 v[58:61], v[38:39], off
	global_load_dwordx4 v[54:57], v[38:39], off offset:1024
	global_load_dwordx4 v[50:53], v[38:39], off offset:2048
	global_load_dwordx4 v[46:49], v[38:39], off offset:3072
	ds_bpermute_b32 v81, v77, v80
	s_waitcnt lgkmcnt(0)
	v_add_f32_e32 v38, v80, v81
	v_mul_f32_e32 v38, 0x3a800000, v38
	v_pk_add_f32 v[44:45], v[44:45], v[38:39] op_sel_hi:[1,0] neg_lo:[0,1] neg_hi:[0,1]
	v_pk_add_f32 v[78:79], v[78:79], v[38:39] op_sel_hi:[1,0] neg_lo:[0,1] neg_hi:[0,1]
	v_pk_mul_f32 v[84:85], v[44:45], v[44:45]
	v_pk_add_f32 v[42:43], v[42:43], v[38:39] op_sel_hi:[1,0] neg_lo:[0,1] neg_hi:[0,1]
	v_pk_mul_f32 v[82:83], v[78:79], v[78:79]
	v_pk_add_f32 v[86:87], v[86:87], v[38:39] op_sel_hi:[1,0] neg_lo:[0,1] neg_hi:[0,1]
	v_pk_add_f32 v[36:37], v[36:37], v[38:39] op_sel_hi:[1,0] neg_lo:[0,1] neg_hi:[0,1]
	v_pk_add_f32 v[34:35], v[34:35], v[38:39] op_sel_hi:[1,0] neg_lo:[0,1] neg_hi:[0,1]
	v_pk_add_f32 v[92:93], v[32:33], v[38:39] op_sel_hi:[1,0] neg_lo:[0,1] neg_hi:[0,1]
	v_pk_add_f32 v[40:41], v[40:41], v[38:39] op_sel_hi:[1,0] neg_lo:[0,1] neg_hi:[0,1]
	v_add_f32_e32 v39, v84, v85
	v_add_f32_e32 v39, v82, v39
	v_pk_mul_f32 v[70:71], v[36:37], v[36:37]
	v_add_f32_e32 v39, v83, v39
	v_add_f32_e32 v39, v70, v39
	v_pk_mul_f32 v[88:89], v[86:87], v[86:87]
	v_add_f32_e32 v39, v71, v39
	v_add_f32_e32 v39, v88, v39
	v_pk_mul_f32 v[32:33], v[92:93], v[92:93]
	v_add_f32_e32 v39, v89, v39
	v_add_f32_e32 v32, v32, v39
	v_pk_mul_f32 v[90:91], v[34:35], v[34:35]
	v_add_f32_e32 v32, v33, v32
	v_add_f32_e32 v32, v90, v32
	v_pk_mul_f32 v[94:95], v[40:41], v[40:41]
	v_add_f32_e32 v32, v91, v32
	v_add_f32_e32 v32, v94, v32
	v_pk_mul_f32 v[80:81], v[42:43], v[42:43]
	v_add_f32_e32 v32, v95, v32
	v_add_f32_e32 v32, v80, v32
	v_add_f32_e32 v32, v81, v32
	ds_bpermute_b32 v33, v63, v32
	s_waitcnt lgkmcnt(0)
	v_add_f32_e32 v32, v32, v33
	ds_bpermute_b32 v33, v73, v32
	s_waitcnt lgkmcnt(0)
	v_add_f32_e32 v32, v32, v33
	ds_bpermute_b32 v33, v74, v32
	s_waitcnt lgkmcnt(0)
	v_add_f32_e32 v32, v32, v33
	ds_bpermute_b32 v33, v75, v32
	s_waitcnt lgkmcnt(0)
	v_add_f32_e32 v32, v32, v33
	ds_bpermute_b32 v33, v76, v32
	s_waitcnt lgkmcnt(0)
	v_add_f32_e32 v32, v32, v33
	ds_bpermute_b32 v33, v77, v32
	s_waitcnt lgkmcnt(0)
	v_add_f32_e32 v32, v32, v33
	v_fmamk_f32 v32, v32, 0x3a800000, v72
	v_rsq_f32_e32 v32, v32
	s_nop 0
	v_pk_mul_f32 v[44:45], v[44:45], v[32:33] op_sel_hi:[1,0]
	v_pk_mul_f32 v[70:71], v[78:79], v[32:33] op_sel_hi:[1,0]
	v_pk_mul_f32 v[36:37], v[36:37], v[32:33] op_sel_hi:[1,0]
	v_pk_mul_f32 v[78:79], v[86:87], v[32:33] op_sel_hi:[1,0]
	v_pk_mul_f32 v[80:81], v[92:93], v[32:33] op_sel_hi:[1,0]
	v_pk_mul_f32 v[34:35], v[34:35], v[32:33] op_sel_hi:[1,0]
	s_waitcnt vmcnt(4)
	v_pk_fma_f32 v[44:45], v[28:29], v[44:45], v[24:25]
	v_pk_fma_f32 v[70:71], v[30:31], v[70:71], v[26:27]
	v_pk_fma_f32 v[36:37], v[20:21], v[36:37], v[12:13]
	v_pk_fma_f32 v[78:79], v[22:23], v[78:79], v[14:15]
	v_pk_fma_f32 v[80:81], v[16:17], v[80:81], v[8:9]
	v_cvt_pk_bf16_f32 v44, v44, v45
	v_cvt_pk_bf16_f32 v45, v70, v71
	v_cvt_pk_bf16_f32 v36, v36, v37
	v_cvt_pk_bf16_f32 v37, v78, v79
	v_pk_fma_f32 v[34:35], v[18:19], v[34:35], v[10:11]
	global_store_dwordx2 v[68:69], v[44:45], off
	global_store_dwordx2 v[68:69], v[36:37], off offset:512
	v_cvt_pk_bf16_f32 v36, v80, v81
	v_cvt_pk_bf16_f32 v37, v34, v35
	global_store_dwordx2 v[68:69], v[36:37], off offset:1024
	v_pk_mul_f32 v[34:35], v[40:41], v[32:33] op_sel_hi:[1,0]
	v_pk_mul_f32 v[36:37], v[42:43], v[32:33] op_sel_hi:[1,0]
	v_pk_fma_f32 v[34:35], v[4:5], v[34:35], v[0:1]
	v_pk_fma_f32 v[36:37], v[6:7], v[36:37], v[2:3]
	v_cvt_pk_bf16_f32 v34, v34, v35
	v_cvt_pk_bf16_f32 v35, v36, v37
	global_store_dwordx2 v[68:69], v[34:35], off offset:1536
	s_and_saveexec_b64 s[6:7], vcc
	s_cbranch_execz .LBB0_1782
	v_mov_b32_e32 v39, v32
	global_store_dwordx2 v[66:67], v[38:39], off
	s_branch .LBB0_1782

; DI int opaque_tid() { int t = threadIdx.x; asm volatile("" : "+v"(t)); return t; }
; DI void ph_ln(const Params& p, int lnidx, bool last) {
;     const int lane = opaque_tid() & 63;
;     const int gw = blockIdx.x * 8 + (opaque_tid() >> 6), nw = gridDim.x * 8;
;     float* H = (float*)(p.ws + OFF_H); bf16_t* HB = (bf16_t*)(p.ws + OFF_HB);
;     const float* G = p.ln_g + (size_t)lnidx * 1024; const float* Bv = p.ln_b + (size_t)lnidx * 1024;
;     f32x4 g[4], bb[4];
; #pragma unroll
;     for (int i = 0; i < 4; ++i) { g[i] = *(const f32x4*)(G + i * 256 + lane * 4); bb[i] = *(const f32x4*)(Bv + i * 256 + lane * 4); }
;     f32x4 nv[4];
;     if (gw < MT) {
; #pragma unroll
;         for (int i = 0; i < 4; ++i) nv[i] = *(const f32x4*)(H + (size_t)gw * 1024 + i * 256 + lane * 4);
;     }
;     for (int m = gw; m < MT; m += nw) {
;         f32x4 v[4];
; #pragma unroll
;         for (int i = 0; i < 4; ++i) v[i] = nv[i];
;         const int mn = min(m + nw, MT - 1);
; #pragma unroll
;         for (int i = 0; i < 4; ++i) nv[i] = *(const f32x4*)(H + (size_t)mn * 1024 + i * 256 + lane * 4);
.LBB0_1993:
	s_or_b64 exec, exec, s[0:1]
	s_waitcnt lgkmcnt(0)
	v_mov_b32_e32 v0, v210
	s_barrier
	s_mov_b32 s0, 0x8040
	v_ashrrev_i32_e32 v1, 6, v210
	v_add_u32_e32 v62, s81, v1
	v_cmp_gt_i32_e32 vcc, s0, v62
	s_and_saveexec_b64 s[0:1], vcc
	s_cbranch_execz .LBB0_1998
	v_lshlrev_b32_e32 v0, 2, v0
	v_and_b32_e32 v48, 0xfc, v0
	v_mov_b32_e32 v65, 0
	v_lshlrev_b32_e32 v64, 2, v48
	v_lshl_add_u64 v[24:25], s[64:65], 0, v[64:65]
	s_mov_b64 s[0:1], 0x3000
	v_lshl_add_u64 v[28:29], s[62:63], 0, v[64:65]
	v_lshl_add_u64 v[26:27], v[24:25], 0, s[0:1]
	v_lshl_add_u64 v[30:31], v[28:29], 0, s[0:1]
	v_ashrrev_i32_e32 v63, 31, v62
	global_load_dwordx4 v[0:3], v[26:27], off offset:3072
	global_load_dwordx4 v[4:7], v[30:31], off offset:3072
	global_load_dwordx4 v[8:11], v[26:27], off offset:2048
	global_load_dwordx4 v[12:15], v[26:27], off offset:1024
	global_load_dwordx4 v[16:19], v[30:31], off offset:2048
	global_load_dwordx4 v[20:23], v[30:31], off offset:1024
	v_lshlrev_b64 v[30:31], 12, v[62:63]
	s_movk_i32 s0, 0x3000
	v_lshl_add_u64 v[30:31], s[16:17], 0, v[30:31]
	v_add_co_u32_e32 v24, vcc, s0, v24
	v_lshl_add_u64 v[50:51], v[30:31], 0, v[64:65]
	s_nop 0
	v_addc_co_u32_e32 v25, vcc, 0, v25, vcc
	global_load_dwordx4 v[44:47], v[50:51], off
	v_add_co_u32_e32 v52, vcc, s0, v28
	global_load_dwordx4 v[24:27], v[24:25], off
	s_nop 0
	v_addc_co_u32_e32 v53, vcc, 0, v29, vcc
	global_load_dwordx4 v[40:43], v[50:51], off offset:1024
	global_load_dwordx4 v[32:35], v[50:51], off offset:2048
	global_load_dwordx4 v[36:39], v[50:51], off offset:3072
	global_load_dwordx4 v[28:31], v[52:53], off
	v_mbcnt_lo_u32_b32 v49, -1, 0
	v_mbcnt_hi_u32_b32 v49, -1, v49
	v_and_b32_e32 v50, 64, v49
	v_xor_b32_e32 v51, 32, v49
	v_lshlrev_b32_e32 v66, 2, v48
	v_add_u32_e32 v48, 64, v50
	v_xor_b32_e32 v52, 16, v49
	v_cmp_lt_i32_e32 vcc, v51, v48
	v_xor_b32_e32 v53, 8, v49
	v_xor_b32_e32 v54, 4, v49
	v_cndmask_b32_e32 v50, v49, v51, vcc
	v_cmp_lt_i32_e32 vcc, v52, v48
	v_xor_b32_e32 v55, 2, v49
	v_xor_b32_e32 v56, 1, v49
	v_cndmask_b32_e32 v51, v49, v52, vcc
	v_cmp_lt_i32_e32 vcc, v53, v48
	s_mov_b64 s[0:1], 0
	s_mov_b32 s4, 0x803f
	v_cndmask_b32_e32 v52, v49, v53, vcc
	v_cmp_lt_i32_e32 vcc, v54, v48
	s_mov_b32 s5, 0x7fc01ff1
	s_movk_i32 s6, 0xdff0
	v_cndmask_b32_e32 v53, v49, v54, vcc
	v_cmp_lt_i32_e32 vcc, v55, v48
	v_mov_b32_e32 v63, 0x3727c5ac
	v_lshl_add_u64 v[68:69], s[16:17], 0, v[64:65]
	v_cndmask_b32_e32 v54, v49, v55, vcc
	v_cmp_lt_i32_e32 vcc, v56, v48
	v_lshlrev_b32_e32 v76, 2, v50
	v_lshlrev_b32_e32 v77, 2, v51
	v_cndmask_b32_e32 v48, v49, v56, vcc
	v_lshlrev_b32_e32 v78, 2, v52
	v_lshlrev_b32_e32 v79, 2, v53
	v_lshlrev_b32_e32 v80, 2, v54
	v_lshlrev_b32_e32 v81, 2, v48
	s_waitcnt vmcnt(5)
	v_mov_b32_e32 v72, v45
	v_mov_b32_e32 v73, v46
	v_mov_b32_e32 v45, v47
	s_waitcnt vmcnt(3)
	v_mov_b32_e32 v70, v41
	v_mov_b32_e32 v71, v42
	v_mov_b32_e32 v41, v43
	s_waitcnt vmcnt(0)
	s_branch .LBB0_1996

; DI void ph_ln(const Params& p, int lnidx, bool last) {
;     ...
;     for (int m = gw; m < MT; m += nw) {
;         f32x4 v[4];
; #pragma unroll
;         for (int i = 0; i < 4; ++i) v[i] = nv[i];
;         const int mn = min(m + nw, MT - 1);
; #pragma unroll
;         for (int i = 0; i < 4; ++i) nv[i] = *(const f32x4*)(H + (size_t)mn * 1024 + i * 256 + lane * 4);
;         float s = 0.f;
; #pragma unroll
;         for (int i = 0; i < 4; ++i) s += (v[i][0] + v[i][1]) + (v[i][2] + v[i][3]);
;         for (int o = 32; o > 0; o >>= 1) s += __shfl_xor(s, o);
;         const float mu = s * (1.0f / 1024.0f);
;         float qv = 0.f;
; #pragma unroll
;         for (int i = 0; i < 4; ++i)
; #pragma unroll
;             for (int e = 0; e < 4; ++e) { const float d = v[i][e] - mu; qv += d * d; }
;         for (int o = 32; o > 0; o >>= 1) qv += __shfl_xor(qv, o);
;         const float rstd = __frsqrt_rn(qv * (1.0f / 1024.0f) + 1e-5f);
;         const int b = m / LT, pos = m - b * LT;
; #pragma unroll
;         for (int i = 0; i < 4; ++i) {
;             const int c = i * 256 + lane * 4;
;             f32x4 y;
; #pragma unroll
;             for (int e = 0; e < 4; ++e) y[e] = (v[i][e] - mu) * rstd * g[i][e] + bb[i][e];
;             if (last) {
;                 if (pos >= 16) *(f32x4*)(p.out + ((size_t)b * 8192 + (pos - 16)) * 1024 + c) = y;
.LBB0_1996:
	v_pk_add_f32 v[42:43], v[72:73], v[44:45]
	v_pk_add_f32 v[46:47], v[70:71], v[40:41]
	v_add_f32_e32 v42, v42, v43
	v_pk_add_f32 v[46:47], v[46:47], v[46:47] op_sel_hi:[0,1]
	v_add_f32_e32 v43, 0, v42
	v_add_f32_e32 v49, v32, v33
	v_add_f32_e32 v51, v34, v35
	v_mov_b32_e32 v48, v36
	v_mov_b32_e32 v50, v37
	v_mov_b32_e32 v46, v38
	v_mov_b32_e32 v42, v39
	v_pk_add_f32 v[48:49], v[48:49], v[50:51]
	v_pk_add_f32 v[42:43], v[46:47], v[42:43]
	v_mov_b32_e32 v67, v62
	v_pk_add_f32 v[42:43], v[48:49], v[42:43]
	v_add_u32_e32 v62, s34, v67
	v_add_f32_e32 v42, v42, v43
	ds_bpermute_b32 v43, v76, v42
	s_waitcnt lgkmcnt(0)
	v_add_f32_e32 v42, v42, v43
	ds_bpermute_b32 v43, v77, v42
	s_waitcnt lgkmcnt(0)
	v_add_f32_e32 v42, v42, v43
	ds_bpermute_b32 v43, v78, v42
	s_waitcnt lgkmcnt(0)
	v_add_f32_e32 v46, v42, v43
	ds_bpermute_b32 v47, v79, v46
	v_min_i32_e32 v42, 0x803f, v62
	v_ashrrev_i32_e32 v43, 31, v42
	v_lshlrev_b64 v[42:43], 12, v[42:43]
	v_lshl_add_u64 v[42:43], v[68:69], 0, v[42:43]
	s_waitcnt lgkmcnt(0)
	v_add_f32_e32 v64, v46, v47
	global_load_dwordx4 v[58:61], v[42:43], off
	global_load_dwordx4 v[54:57], v[42:43], off offset:1024
	global_load_dwordx4 v[50:53], v[42:43], off offset:2048
	global_load_dwordx4 v[46:49], v[42:43], off offset:3072
	ds_bpermute_b32 v74, v80, v64
	v_mov_b32_e32 v42, v44
	v_mov_b32_e32 v43, v72
	v_mov_b32_e32 v44, v73
	s_waitcnt lgkmcnt(0)
	v_add_f32_e32 v64, v64, v74
	ds_bpermute_b32 v74, v81, v64
	s_waitcnt lgkmcnt(0)
	v_add_f32_e32 v64, v64, v74
	v_mul_f32_e32 v64, 0x3a800000, v64
	v_pk_add_f32 v[72:73], v[42:43], v[64:65] op_sel_hi:[1,0] neg_lo:[0,1] neg_hi:[0,1]
	v_pk_add_f32 v[74:75], v[44:45], v[64:65] op_sel_hi:[1,0] neg_lo:[0,1] neg_hi:[0,1]
	v_pk_mul_f32 v[82:83], v[72:73], v[72:73]
	v_mov_b32_e32 v42, v40
	v_mov_b32_e32 v43, v70
	v_mov_b32_e32 v40, v71
	v_pk_mul_f32 v[84:85], v[74:75], v[74:75]
	v_pk_add_f32 v[44:45], v[42:43], v[64:65] op_sel_hi:[1,0] neg_lo:[0,1] neg_hi:[0,1]
	v_pk_add_f32 v[70:71], v[40:41], v[64:65] op_sel_hi:[1,0] neg_lo:[0,1] neg_hi:[0,1]
	v_pk_add_f32 v[40:41], v[32:33], v[64:65] op_sel_hi:[1,0] neg_lo:[0,1] neg_hi:[0,1]
	v_pk_add_f32 v[42:43], v[34:35], v[64:65] op_sel_hi:[1,0] neg_lo:[0,1] neg_hi:[0,1]
	v_pk_add_f32 v[32:33], v[36:37], v[64:65] op_sel_hi:[1,0] neg_lo:[0,1] neg_hi:[0,1]
	v_pk_add_f32 v[34:35], v[38:39], v[64:65] op_sel_hi:[1,0] neg_lo:[0,1] neg_hi:[0,1]
	v_add_f32_e32 v64, v82, v83
	v_add_f32_e32 v64, v84, v64
	v_pk_mul_f32 v[86:87], v[44:45], v[44:45]
	v_add_f32_e32 v64, v85, v64
	v_add_f32_e32 v64, v86, v64
	v_pk_mul_f32 v[88:89], v[70:71], v[70:71]
	v_add_f32_e32 v64, v87, v64
	v_add_f32_e32 v64, v88, v64
	v_pk_mul_f32 v[90:91], v[40:41], v[40:41]
	v_add_f32_e32 v64, v89, v64
	v_add_f32_e32 v64, v90, v64
	v_pk_mul_f32 v[92:93], v[42:43], v[42:43]
	v_add_f32_e32 v64, v91, v64
	v_add_f32_e32 v64, v92, v64
	v_pk_mul_f32 v[36:37], v[32:33], v[32:33]
	v_add_f32_e32 v64, v93, v64
	v_add_f32_e32 v36, v36, v64
	v_pk_mul_f32 v[38:39], v[34:35], v[34:35]
	v_add_f32_e32 v36, v37, v36
	v_add_f32_e32 v36, v38, v36
	v_add_f32_e32 v36, v39, v36
	ds_bpermute_b32 v37, v76, v36
	v_mul_hi_i32 v39, v67, s5
	s_waitcnt lgkmcnt(0)
	v_add_f32_e32 v36, v36, v37
	ds_bpermute_b32 v37, v77, v36
	s_waitcnt lgkmcnt(0)
	v_add_f32_e32 v36, v36, v37
	ds_bpermute_b32 v37, v78, v36
	s_waitcnt lgkmcnt(0)
	v_add_f32_e32 v36, v36, v37
	ds_bpermute_b32 v37, v79, v36
	s_waitcnt lgkmcnt(0)
	v_add_f32_e32 v36, v36, v37
	ds_bpermute_b32 v37, v80, v36
	s_waitcnt lgkmcnt(0)
	v_add_f32_e32 v37, v36, v37
	ds_bpermute_b32 v38, v81, v37
	v_lshrrev_b32_e32 v36, 31, v39
	v_ashrrev_i32_e32 v39, 12, v39
	v_add_u32_e32 v36, v39, v36
	v_mad_i32_i24 v39, v36, s6, v67
	v_cmp_lt_i32_e32 vcc, 15, v39
	s_and_saveexec_b64 s[2:3], vcc
	s_cbranch_execz .LBB0_1995
	s_waitcnt lgkmcnt(0)
	v_add_f32_e32 v37, v37, v38
	v_fmamk_f32 v37, v37, 0x3a800000, v63
	v_rsq_f32_e32 v82, v37
	v_ashrrev_i32_e32 v37, 31, v36
	v_add_u32_e32 v64, -16, v39
	v_lshlrev_b64 v[86:87], 25, v[36:37]
	v_lshlrev_b64 v[84:85], 12, v[64:65]
	v_pk_mul_f32 v[36:37], v[72:73], v[82:83] op_sel_hi:[1,0]
	v_lshl_add_u64 v[72:73], s[54:55], 0, v[86:87]
	v_pk_mul_f32 v[38:39], v[74:75], v[82:83] op_sel_hi:[1,0]
	v_lshl_add_u64 v[72:73], v[72:73], 0, v[84:85]
	v_mov_b32_e32 v67, v65
	s_waitcnt vmcnt(4)
	v_pk_fma_f32 v[38:39], v[30:31], v[38:39], v[26:27]
	v_pk_fma_f32 v[36:37], v[28:29], v[36:37], v[24:25]
	v_lshl_add_u64 v[72:73], v[72:73], 0, v[66:67]
	global_store_dwordx4 v[72:73], v[36:39], off
	v_pk_mul_f32 v[32:33], v[32:33], v[82:83] op_sel_hi:[1,0]
	v_pk_mul_f32 v[34:35], v[34:35], v[82:83] op_sel_hi:[1,0]
	v_pk_mul_f32 v[36:37], v[44:45], v[82:83] op_sel_hi:[1,0]
	v_pk_mul_f32 v[38:39], v[70:71], v[82:83] op_sel_hi:[1,0]
	v_pk_fma_f32 v[36:37], v[20:21], v[36:37], v[12:13]
	v_pk_fma_f32 v[38:39], v[22:23], v[38:39], v[14:15]
	global_store_dwordx4 v[72:73], v[36:39], off offset:1024
	v_pk_fma_f32 v[34:35], v[6:7], v[34:35], v[2:3]
	v_pk_fma_f32 v[32:33], v[4:5], v[32:33], v[0:1]
	v_pk_mul_f32 v[36:37], v[40:41], v[82:83] op_sel_hi:[1,0]
	v_pk_mul_f32 v[38:39], v[42:43], v[82:83] op_sel_hi:[1,0]
	v_pk_fma_f32 v[36:37], v[16:17], v[36:37], v[8:9]
	v_pk_fma_f32 v[38:39], v[18:19], v[38:39], v[10:11]
	global_store_dwordx4 v[72:73], v[36:39], off offset:2048
	global_store_dwordx4 v[72:73], v[32:35], off offset:3072
	s_branch .LBB0_1995
